# v55: IN unit order permuted so the 4th (partial) round contains only plain-store tiles; its 23 sigmoid-epilogue tiles swap places with plain tiles of WGs that have only 3 units
# baseline (speedup 1.0000x reference)
;     __device__ __forceinline__ bool next(int i, int& pm, int& pn, int& k0, int& nk, int& slice, int& src) const {
;         const long L = (long)i * G + c;
;         pm = 0; pn = 0; k0 = 0; nk = nt; slice = -1; src = 0;
;         if (L < nwg) {
;             int wgid = (int)L; { const int q = nwg / NXCD, r = nwg % NXCD, xcd = wgid % NXCD, off = wgid / NXCD; wgid = (xcd < r ? xcd * (q + 1) : r * (q + 1) + (xcd - r) * q) + off; }
;             const int nig = WGM * nN, gid = wgid / nig, fm = gid * WGM, gsz = (nM - fm) < WGM ? (nM - fm) : WGM;
;             pm = fm + ((wgid % nig) % gsz); pn = (wgid % nig) / gsz; return true;
; template <int EPI> ...
;     ...
;     if (!S.next(0, cur_pm, cur_pn, cur_k0, cur_nk, cur_slice, cur_src)) return;
.LBB0_118:
	s_or_b64 exec, exec, s[0:1]
	v_readlane_b32 s3, v244, 33
	v_mov_b32_e32 v10, v0
	s_cmpk_lt_i32 s3, 0x35a
	s_waitcnt lgkmcnt(0)
	s_barrier
	s_mov_b32 s4, 0
	v_readfirstlane_b32 s12, v10
	s_cselect_b64 s[0:1], -1, 0
	s_cmpk_gt_i32 s3, 0x359
	s_mov_b32 s6, 0
	s_cbranch_scc1 .LBB0_124
	v_readlane_b32 s5, v244, 33
	s_nop 3
	s_cmp_lg_u32 s33, 0x100
	s_cbranch_scc1 .Lpina_done
	s_and_b32 s98, s5, 7
	s_lshr_b32 s99, s5, 3
	s_cmp_eq_u32 s98, 0
	s_cbranch_scc0 .Lpina_1
	s_sub_u32 s99, s99, 24
	s_cmp_lt_u32 s99, 8
	s_cbranch_scc0 .Lpina_done
	s_add_u32 s5, s5, 576
	s_branch .Lpina_done
.Lpina_1:
	s_cmp_eq_u32 s98, 1
	s_cbranch_scc0 .Lpina_7
	s_sub_u32 s99, s99, 28
	s_cmp_lt_u32 s99, 4
	s_cbranch_scc0 .Lpina_done
	s_add_u32 s5, s5, 544
	s_branch .Lpina_done
.Lpina_7:
	s_cmp_eq_u32 s5, 135
	s_cbranch_scc0 .Lpina_done
	s_movk_i32 s5, 855
.Lpina_done:
	s_ashr_i32 s3, s5, 31
	s_lshr_b32 s3, s3, 29
	s_add_i32 s3, s5, s3
	s_and_b32 s4, s3, -8
	s_sub_i32 s6, s5, s4
	s_cmp_gt_i32 s6, 1
	s_cbranch_scc0 .LBB0_121
	s_mul_i32 s4, s6, 0x6b
	s_add_i32 s7, s4, 2
	s_cbranch_execz .LBB0_122
	s_branch .LBB0_123

;     __device__ __forceinline__ bool next(int i, int& pm, int& pn, int& k0, int& nk, int& slice, int& src) const {
;         const long L = (long)i * G + c;
;         pm = 0; pn = 0; k0 = 0; nk = nt; slice = -1; src = 0;
;         if (L < nwg) {
;             int wgid = (int)L; { const int q = nwg / NXCD, r = nwg % NXCD, xcd = wgid % NXCD, off = wgid / NXCD; wgid = (xcd < r ? xcd * (q + 1) : r * (q + 1) + (xcd - r) * q) + off; }
;             const int nig = WGM * nN, gid = wgid / nig, fm = gid * WGM, gsz = (nM - fm) < WGM ? (nM - fm) : WGM;
;             pm = fm + ((wgid % nig) % gsz); pn = (wgid % nig) / gsz; return true;
; template <int EPI> ...
;     ...
;     for (;;) {
;         const bool has_next = S.next(ui + 1, nxt_pm, nxt_pn, nxt_k0, nxt_nk, nxt_slice, nxt_src);
;         const char* nA = has_next ? (const char*)((EPI == EPI_GLU && nxt_src) ? gA2 : gA) + (size_t)nxt_pm * tstep + (size_t)nxt_k0 * kstep : cA;
;         const char* nB = has_next ? (const char*)((EPI == EPI_GLU && nxt_src) ? gBt2 : gBt) + (size_t)nxt_pn * tstep + (size_t)nxt_k0 * kstep : cB;
.LBB0_130:
	s_add_i32 s46, s46, 1
	s_mul_i32 s0, s46, s50
	s_mul_hi_u32 s1, s46, s33
	s_add_i32 s1, s1, s0
	s_mul_i32 s0, s46, s33
	v_readlane_b32 s5, v244, 33
	s_add_u32 s22, s0, s5
	v_readlane_b32 s0, v244, 59
	s_addc_u32 s23, s1, s0
	v_cmp_gt_i64_e32 vcc, s[22:23], v[162:163]
	v_cmp_lt_i64_e64 s[0:1], s[22:23], v[160:161]
	s_mov_b32 s18, 0
	s_mov_b32 s20, 0
	s_cbranch_vccnz .LBB0_136
	s_cmp_lg_u32 s33, 0x100
	s_cbranch_scc1 .Lpinb_done
	s_and_b32 s98, s22, 7
	s_lshr_b32 s99, s22, 3
	s_cmp_eq_u32 s98, 0
	s_cbranch_scc0 .Lpinb_1
	s_sub_u32 s99, s99, 96
	s_cmp_lt_u32 s99, 8
	s_cbranch_scc0 .Lpinb_done
	s_sub_u32 s22, s22, 576
	s_branch .Lpinb_done
.Lpinb_1:
	s_cmp_eq_u32 s98, 1
	s_cbranch_scc0 .Lpinb_7
	s_sub_u32 s99, s99, 96
	s_cmp_lt_u32 s99, 4
	s_cbranch_scc0 .Lpinb_done
	s_sub_u32 s22, s22, 544
	s_branch .Lpinb_done
.Lpinb_7:
	s_cmp_eq_u32 s98, 7
	s_cbranch_scc0 .Lpinb_done
	s_cmp_eq_u32 s22, 855
	s_cbranch_scc0 .Lpinb_7b
	s_movk_i32 s22, 135
	s_branch .Lpinb_done
.Lpinb_7b:
	s_sub_u32 s98, s99, 96
	s_cmp_lt_u32 s98, 10
	s_cbranch_scc0 .Lpinb_7c
	s_sub_u32 s22, s22, 120
	s_branch .Lpinb_done
.Lpinb_7c:
	s_sub_u32 s98, s99, 81
	s_cmp_lt_u32 s98, 10
	s_cbranch_scc0 .Lpinb_done
	s_add_u32 s22, s22, 120
.Lpinb_done:
	s_ashr_i32 s5, s22, 31
	s_lshr_b32 s5, s5, 29
	s_add_i32 s5, s22, s5
	s_and_b32 s7, s5, -8
	s_sub_i32 s7, s22, s7
	s_cmp_gt_i32 s7, 1
	s_mov_b64 s[18:19], -1
	s_cbranch_scc0 .LBB0_133
	s_mul_i32 s18, s7, 0x6b
	s_add_i32 s20, s18, 2
	s_mov_b64 s[18:19], 0
